# select: 64 distinct queries per wave step (was 32 duplicated on both half-waves), 4 steps instead of 8
# speedup vs baseline: 1.0130x; 1.0130x over previous
.LBB0_161:
	s_or_b64 exec, exec, s[0:1]
	s_cmpk_lt_i32 s2, 0x100
	s_cselect_b64 s[40:41], -1, 0
	s_cmpk_gt_i32 s2, 0xff
	s_barrier
	s_cbranch_scc1 .LBB0_187
	v_lshlrev_b64 v[0:1], v189, -1
	v_readlane_b32 s8, v254, 57
	v_not_b32_e32 v64, v0
	v_mov_b32_e32 v131, 0
	v_readlane_b32 s12, v254, 61
	v_readlane_b32 s13, v254, 62
	v_mbcnt_lo_u32_b32 v0, -1, 0
	v_xor_b32_e32 v68, 15, v196
	v_cmp_gt_u32_e64 s[4:5], 64, v189
	v_not_b32_e32 v65, v1
	v_lshl_or_b32 v69, v196, 8, v189
	v_add_u32_e32 v70, 0xfffffe00, v188
	v_add_u32_e32 v71, 0, v130
	v_lshl_add_u64 v[66:67], s[12:13], 0, v[130:131]
	v_mbcnt_hi_u32_b32 v72, -1, v0
	v_mov_b32_e32 v73, 0x2000
	v_mov_b32_e32 v74, 0x1000
	s_mov_b32 s33, s2
	v_readlane_b32 s9, v254, 58
	v_readlane_b32 s10, v254, 59
	v_readlane_b32 s11, v254, 60
	v_readlane_b32 s14, v254, 63
	v_readlane_b32 s15, v255, 0
	v_readlane_b32 s16, v255, 1
	v_readlane_b32 s17, v255, 2
	v_readlane_b32 s18, v255, 3
	v_readlane_b32 s19, v255, 4
	v_readlane_b32 s20, v255, 5
	v_readlane_b32 s21, v255, 6
	v_readlane_b32 s22, v255, 7
	v_readlane_b32 s23, v255, 8
	s_branch .LBB0_164

.LBB0_165:
	global_load_dword v4, v[0:1], off
	v_add_co_u32_e32 v3, vcc, 0x200, v3
	s_mov_b64 s[8:9], 0x800
	v_lshl_add_u64 v[0:1], v[0:1], 0, s[8:9]
	s_xor_b64 s[8:9], vcc, -1
	s_and_b64 s[8:9], exec, s[8:9]
	s_or_b64 s[6:7], s[8:9], s[6:7]
	s_waitcnt vmcnt(0)
	ds_write_b32 v2, v4
	v_add_u32_e32 v2, 0x800, v2
	s_andn2_b64 exec, exec, s[6:7]
	s_cbranch_execnz .LBB0_165
	s_or_b64 exec, exec, s[6:7]
	s_and_b32 s1, s33, 1
	v_lshl_or_b32 v0, s1, 7, v69
	v_or_b32_e32 v0, s10, v0
	v_mov_b32_e32 v1, s11
	v_lshlrev_b64 v[0:1], 7, v[0:1]
	v_lshl_add_u64 v[0:1], s[64:65], 0, v[0:1]
	s_waitcnt lgkmcnt(0)
	s_barrier
	global_load_dwordx4 v[60:63], v[0:1], off
	global_load_dwordx4 v[56:59], v[0:1], off offset:16
	global_load_dwordx4 v[52:55], v[0:1], off offset:32
	global_load_dwordx4 v[48:51], v[0:1], off offset:48
	global_load_dwordx4 v[44:47], v[0:1], off offset:64
	global_load_dwordx4 v[40:43], v[0:1], off offset:80
	global_load_dwordx4 v[36:39], v[0:1], off offset:96
	global_load_dwordx4 v[32:35], v[0:1], off offset:112
	s_lshl_b32 s0, s0, 4
	s_lshl_b32 s34, s1, 1
	s_ashr_i32 s1, s0, 31
	v_readlane_b32 s12, v254, 57
	s_lshl_b64 s[6:7], s[0:1], 2
	v_readlane_b32 s22, v255, 3
	v_readlane_b32 s13, v254, 58
	v_readlane_b32 s23, v255, 4
	s_add_u32 s12, s22, s6
	v_readlane_b32 s14, v254, 59
	v_readlane_b32 s24, v255, 5
	s_addc_u32 s13, s23, s7
	s_lshl_b64 s[0:1], s[0:1], 13
	v_readlane_b32 s15, v254, 60
	v_readlane_b32 s20, v255, 1
	v_readlane_b32 s25, v255, 6
	s_add_u32 s14, s24, s0
	s_addc_u32 s15, s25, s1
	s_mov_b32 s20, 0
	v_readlane_b32 s16, v254, 61
	v_readlane_b32 s17, v254, 62
	v_readlane_b32 s18, v254, 63
	v_readlane_b32 s19, v255, 0
	v_readlane_b32 s21, v255, 2
	v_readlane_b32 s26, v255, 7
	v_readlane_b32 s27, v255, 8
	s_branch .LBB0_168
.LBB0_167:
	s_or_b64 exec, exec, s[16:17]
	s_cmp_eq_u32 s35, 4
	s_mov_b32 s20, s35
	s_waitcnt vmcnt(7)
	v_mov_b32_e32 v60, v28
	v_mov_b32_e32 v61, v29
	v_mov_b32_e32 v62, v30
	v_mov_b32_e32 v63, v31
	s_waitcnt vmcnt(6)
	v_mov_b32_e32 v56, v24
	v_mov_b32_e32 v57, v25
	v_mov_b32_e32 v58, v26
	v_mov_b32_e32 v59, v27
	s_waitcnt vmcnt(5)
	v_mov_b32_e32 v52, v20
	v_mov_b32_e32 v53, v21
	v_mov_b32_e32 v54, v22
	v_mov_b32_e32 v55, v23
	s_waitcnt vmcnt(4)
	v_mov_b32_e32 v48, v16
	v_mov_b32_e32 v49, v17
	v_mov_b32_e32 v50, v18
	v_mov_b32_e32 v51, v19
	s_waitcnt vmcnt(3)
	v_mov_b32_e32 v44, v12
	v_mov_b32_e32 v45, v13
	v_mov_b32_e32 v46, v14
	v_mov_b32_e32 v47, v15
	s_waitcnt vmcnt(2)
	v_mov_b32_e32 v40, v8
	v_mov_b32_e32 v41, v9
	v_mov_b32_e32 v42, v10
	v_mov_b32_e32 v43, v11
	s_waitcnt vmcnt(1)
	v_mov_b32_e32 v36, v4
	v_mov_b32_e32 v37, v5
	v_mov_b32_e32 v38, v6
	v_mov_b32_e32 v39, v7
	s_waitcnt vmcnt(0)
	v_mov_b32_e32 v32, v0
	s_waitcnt lgkmcnt(0)
	v_mov_b32_e32 v33, v1
	v_mov_b32_e32 v34, v2
	v_mov_b32_e32 v35, v3
	s_cbranch_scc1 .LBB0_163
.LBB0_168:
	s_cmp_lt_u32 s20, 2
	s_cselect_b64 vcc, -1, 0
	s_add_i32 s35, s20, 1
	s_cmp_lg_u32 s20, 3
	s_cselect_b32 s6, s35, 3
	s_cmp_lt_u32 s6, 2
	s_cselect_b64 s[0:1], -1, 0
	v_cndmask_b32_e64 v0, v68, v196, s[0:1]
	s_and_b32 s0, s6, 1
	s_or_b32 s0, s0, s34
	s_lshl_b32 s0, s0, 6
	v_lshl_or_b32 v0, v0, 8, s0
	v_or3_b32 v0, v0, v189, s10
	v_mov_b32_e32 v1, s11
	v_lshlrev_b64 v[0:1], 7, v[0:1]
	v_lshl_add_u64 v[0:1], s[64:65], 0, v[0:1]
	global_load_dwordx4 v[28:31], v[0:1], off
	global_load_dwordx4 v[24:27], v[0:1], off offset:16
	global_load_dwordx4 v[20:23], v[0:1], off offset:32
	global_load_dwordx4 v[16:19], v[0:1], off offset:48
	global_load_dwordx4 v[12:15], v[0:1], off offset:64
	global_load_dwordx4 v[8:11], v[0:1], off offset:80
	global_load_dwordx4 v[4:7], v[0:1], off offset:96
	s_nop 0
	global_load_dwordx4 v[0:3], v[0:1], off offset:112
	v_cndmask_b32_e32 v75, v68, v196, vcc
	v_cmp_ne_u32_e32 vcc, 0, v75
	s_and_saveexec_b64 s[16:17], vcc
	s_cbranch_execz .LBB0_167
	s_waitcnt vmcnt(15)
	v_lshlrev_b32_e32 v76, 16, v60
	v_and_b32_e32 v60, 0xffff0000, v60
	v_lshlrev_b32_e32 v77, 16, v61
	v_and_b32_e32 v61, 0xffff0000, v61
	v_lshlrev_b32_e32 v78, 16, v62
	v_and_b32_e32 v62, 0xffff0000, v62
	v_lshlrev_b32_e32 v79, 16, v63
	v_and_b32_e32 v63, 0xffff0000, v63
	s_waitcnt vmcnt(14)
	v_lshlrev_b32_e32 v80, 16, v56
	v_and_b32_e32 v56, 0xffff0000, v56
	v_lshlrev_b32_e32 v81, 16, v57
	v_and_b32_e32 v57, 0xffff0000, v57
	v_lshlrev_b32_e32 v82, 16, v58
	v_and_b32_e32 v58, 0xffff0000, v58
	v_lshlrev_b32_e32 v83, 16, v59
	v_and_b32_e32 v59, 0xffff0000, v59
	s_waitcnt vmcnt(13)
	v_lshlrev_b32_e32 v84, 16, v52
	v_and_b32_e32 v52, 0xffff0000, v52
	v_lshlrev_b32_e32 v85, 16, v53
	v_and_b32_e32 v53, 0xffff0000, v53
	v_lshlrev_b32_e32 v86, 16, v54
	v_and_b32_e32 v54, 0xffff0000, v54
	v_lshlrev_b32_e32 v87, 16, v55
	v_and_b32_e32 v55, 0xffff0000, v55
	s_waitcnt vmcnt(12)
	v_lshlrev_b32_e32 v88, 16, v48
	v_and_b32_e32 v48, 0xffff0000, v48
	v_lshlrev_b32_e32 v89, 16, v49
	v_and_b32_e32 v49, 0xffff0000, v49
	v_lshlrev_b32_e32 v90, 16, v50
	v_and_b32_e32 v50, 0xffff0000, v50
	v_lshlrev_b32_e32 v91, 16, v51
	v_and_b32_e32 v51, 0xffff0000, v51
	s_waitcnt vmcnt(11)
	v_lshlrev_b32_e32 v92, 16, v44
	v_and_b32_e32 v93, 0xffff0000, v44
	v_lshlrev_b32_e32 v94, 16, v45
	v_and_b32_e32 v95, 0xffff0000, v45
	v_lshlrev_b32_e32 v96, 16, v46
	v_and_b32_e32 v46, 0xffff0000, v46
	v_lshlrev_b32_e32 v97, 16, v47
	v_and_b32_e32 v47, 0xffff0000, v47
	s_waitcnt vmcnt(10)
	v_lshlrev_b32_e32 v98, 16, v40
	v_and_b32_e32 v99, 0xffff0000, v40
	v_lshlrev_b32_e32 v100, 16, v41
	v_and_b32_e32 v101, 0xffff0000, v41
	v_lshlrev_b32_e32 v102, 16, v42
	v_and_b32_e32 v103, 0xffff0000, v42
	v_lshlrev_b32_e32 v104, 16, v43
	v_and_b32_e32 v105, 0xffff0000, v43
	s_waitcnt vmcnt(9)
	v_lshlrev_b32_e32 v106, 16, v36
	v_and_b32_e32 v107, 0xffff0000, v36
	v_lshlrev_b32_e32 v108, 16, v37
	v_and_b32_e32 v109, 0xffff0000, v37
	v_and_b32_e32 v37, 0xffff0000, v38
	v_lshlrev_b32_e32 v36, 16, v38
	v_and_b32_e32 v41, 0xffff0000, v39
	v_lshlrev_b32_e32 v40, 16, v39
	s_waitcnt vmcnt(8)
	v_and_b32_e32 v39, 0xffff0000, v32
	v_lshlrev_b32_e32 v38, 16, v32
	v_and_b32_e32 v43, 0xffff0000, v33
	v_lshlrev_b32_e32 v42, 16, v33
	v_and_b32_e32 v33, 0xffff0000, v34
	v_lshlrev_b32_e32 v32, 16, v34
	v_and_b32_e32 v45, 0xffff0000, v35
	v_lshlrev_b32_e32 v44, 16, v35
	v_mov_b32_e32 v35, -1
	s_mov_b32 s21, 0
	v_mov_b32_e32 v110, 0xff800000
	s_mov_b32 s22, 0
	s_mov_b64 s[0:1], 0
	v_mov_b32_e32 v111, 0xff800000
	v_mov_b32_e32 v34, -1
	v_mov_b32_e32 v112, -1
	v_mov_b32_e32 v113, 0xff800000
	s_branch .LBB0_173

.LBB0_177:
	s_or_b64 exec, exec, s[0:1]
	s_and_b32 s0, s20, 1
	s_or_b32 s0, s0, s34
	s_lshl_b32 s0, s0, 6
	v_lshlrev_b32_e32 v32, 8, v75
	v_or3_b32 v32, s0, v32, v189
	s_mov_b64 s[18:19], 0
	s_mov_b64 s[20:21], s[14:15]
	s_mov_b64 s[22:23], s[12:13]
	v_mov_b32_e32 v140, v114
	v_mov_b32_e32 v141, v34
	v_mov_b32_e32 v142, v35
	v_mov_b32_e32 v143, 0
	v_lshlrev_b32_e32 v147, 2, v189
	v_readfirstlane_b32 s73, v75
	s_mov_b32 s72, 0
